# converter: flat_load -> global_load nt so item B loads overlap item A (no lgkmcnt serialization)
# speedup vs baseline: 1.0004x; 1.0004x over previous
.LBB0_108:
	v_add_u32_e32 v72, s10, v66
	v_cmp_ne_u64_e32 vcc, 0, v[34:35]
	v_mov_b32_e32 v2, 0
	v_ashrrev_i32_e32 v73, 31, v72
	v_mov_b32_e32 v14, 0
	v_mov_b32_e32 v15, 0
	v_mov_b32_e32 v16, 0
	v_mov_b32_e32 v17, 0
	s_and_saveexec_b64 s[16:17], vcc
	s_cbranch_execz .LBB0_110
	v_mul_lo_u32 v0, s19, v72
	v_mul_lo_u32 v3, s18, v73
	v_mad_u64_u32 v[4:5], s[20:21], s18, v72, 0
	v_add3_u32 v5, v5, v3, v0
	v_lshl_add_u64 v[4:5], v[4:5], 2, v[34:35]
	global_load_dwordx4 v[14:17], v[4:5], off nt
.LBB0_110:
	s_or_b64 exec, exec, s[16:17]
	v_mov_b32_e32 v3, 0
	v_mov_b32_e32 v4, 0
	v_mov_b32_e32 v5, 0
	s_and_saveexec_b64 s[16:17], vcc
	s_cbranch_execz .LBB0_112
	v_add_u32_e32 v0, 32, v72
	v_ashrrev_i32_e32 v2, 31, v0
	v_mul_lo_u32 v4, s18, v2
	v_mul_lo_u32 v5, s19, v0
	v_mad_u64_u32 v[2:3], s[20:21], s18, v0, 0
	v_add3_u32 v3, v3, v4, v5
	v_lshl_add_u64 v[2:3], v[2:3], 2, v[34:35]
	global_load_dwordx4 v[2:5], v[2:3], off nt
.LBB0_112:
	s_or_b64 exec, exec, s[16:17]
	v_mov_b32_e32 v6, 0
	v_mov_b32_e32 v22, 0
	v_mov_b32_e32 v23, 0
	v_mov_b32_e32 v24, 0
	v_mov_b32_e32 v25, 0
	s_and_saveexec_b64 s[16:17], vcc
	s_cbranch_execz .LBB0_114
	v_add_u32_e32 v0, 64, v72
	v_ashrrev_i32_e32 v7, 31, v0
	v_mul_lo_u32 v7, s18, v7
	v_mul_lo_u32 v10, s19, v0
	v_mad_u64_u32 v[8:9], s[20:21], s18, v0, 0
	v_add3_u32 v9, v9, v7, v10
	v_lshl_add_u64 v[8:9], v[8:9], 2, v[34:35]
	global_load_dwordx4 v[22:25], v[8:9], off nt
.LBB0_114:
	s_or_b64 exec, exec, s[16:17]
	v_mov_b32_e32 v7, 0
	v_mov_b32_e32 v8, 0
	v_mov_b32_e32 v9, 0
	s_and_saveexec_b64 s[16:17], vcc
	s_cbranch_execz .LBB0_116
	v_add_u32_e32 v0, 0x60, v72
	v_ashrrev_i32_e32 v6, 31, v0
	v_mul_lo_u32 v8, s18, v6
	v_mul_lo_u32 v9, s19, v0
	v_mad_u64_u32 v[6:7], s[20:21], s18, v0, 0
	v_add3_u32 v7, v7, v8, v9
	v_lshl_add_u64 v[6:7], v[6:7], 2, v[34:35]
	global_load_dwordx4 v[6:9], v[6:7], off nt
.LBB0_116:
	s_or_b64 exec, exec, s[16:17]
	v_mov_b32_e32 v18, 0
	v_mov_b32_e32 v26, 0
	v_mov_b32_e32 v27, 0
	v_mov_b32_e32 v28, 0
	v_mov_b32_e32 v29, 0
	s_and_saveexec_b64 s[16:17], vcc
	s_cbranch_execz .LBB0_118
	v_add_u32_e32 v0, 0x80, v72
	v_ashrrev_i32_e32 v10, 31, v0
	v_mul_lo_u32 v12, s18, v10
	v_mul_lo_u32 v13, s19, v0
	v_mad_u64_u32 v[10:11], s[20:21], s18, v0, 0
	v_add3_u32 v11, v11, v12, v13
	v_lshl_add_u64 v[10:11], v[10:11], 2, v[34:35]
	global_load_dwordx4 v[26:29], v[10:11], off nt
.LBB0_118:
	s_or_b64 exec, exec, s[16:17]
	v_mov_b32_e32 v19, 0
	v_mov_b32_e32 v20, 0
	v_mov_b32_e32 v21, 0
	s_and_saveexec_b64 s[16:17], vcc
	s_cbranch_execz .LBB0_120
	v_add_u32_e32 v0, 0xa0, v72
	v_ashrrev_i32_e32 v10, 31, v0
	v_mul_lo_u32 v12, s18, v10
	v_mul_lo_u32 v13, s19, v0
	v_mad_u64_u32 v[10:11], s[20:21], s18, v0, 0
	v_add3_u32 v11, v11, v12, v13
	v_lshl_add_u64 v[10:11], v[10:11], 2, v[34:35]
	global_load_dwordx4 v[18:21], v[10:11], off nt
.LBB0_120:
	s_or_b64 exec, exec, s[16:17]
	v_mov_b32_e32 v10, 0
	v_mov_b32_e32 v30, 0
	v_mov_b32_e32 v31, 0
	v_mov_b32_e32 v32, 0
	v_mov_b32_e32 v33, 0
	s_and_saveexec_b64 s[16:17], vcc
	s_cbranch_execz .LBB0_122
	v_add_u32_e32 v0, 0xc0, v72
	v_ashrrev_i32_e32 v11, 31, v0
	v_mul_lo_u32 v11, s18, v11
	v_mul_lo_u32 v30, s19, v0
	v_mad_u64_u32 v[12:13], s[20:21], s18, v0, 0
	v_add3_u32 v13, v13, v11, v30
	v_lshl_add_u64 v[12:13], v[12:13], 2, v[34:35]
	global_load_dwordx4 v[30:33], v[12:13], off nt
.LBB0_122:
	s_or_b64 exec, exec, s[16:17]
	v_mov_b32_e32 v11, 0
	v_mov_b32_e32 v12, 0
	v_mov_b32_e32 v13, 0
	s_and_saveexec_b64 s[16:17], vcc
	s_cbranch_execz .LBB0_124
	v_add_u32_e32 v0, 0xe0, v72
	v_ashrrev_i32_e32 v10, 31, v0
	v_mul_lo_u32 v12, s18, v10
	v_mul_lo_u32 v13, s19, v0
	v_mad_u64_u32 v[10:11], s[18:19], s18, v0, 0
	v_add3_u32 v11, v11, v12, v13
	v_lshl_add_u64 v[10:11], v[10:11], 2, v[34:35]
	global_load_dwordx4 v[10:13], v[10:11], off nt

.LBB0_175:
	v_cmp_ne_u64_e32 vcc, 0, v[74:75]
	v_add_u32_e32 v0, s20, v66
	v_mov_b32_e32 v34, 0
	v_mov_b32_e32 v38, 0
	v_mov_b32_e32 v39, 0
	v_mov_b32_e32 v40, 0
	v_mov_b32_e32 v41, 0
	s_and_saveexec_b64 s[24:25], vcc
	s_cbranch_execz .LBB0_177
	v_ashrrev_i32_e32 v35, 31, v0
	v_mul_lo_u32 v38, s27, v0
	v_mul_lo_u32 v35, s26, v35
	v_mad_u64_u32 v[36:37], s[30:31], s26, v0, 0
	v_add3_u32 v37, v37, v35, v38
	v_lshl_add_u64 v[36:37], v[36:37], 2, v[74:75]
	global_load_dwordx4 v[38:41], v[36:37], off nt
.LBB0_177:
	s_or_b64 exec, exec, s[24:25]
	v_mov_b32_e32 v35, 0
	v_mov_b32_e32 v36, 0
	v_mov_b32_e32 v37, 0
	s_and_saveexec_b64 s[24:25], vcc
	s_cbranch_execz .LBB0_179
	v_add_u32_e32 v34, 32, v0
	v_ashrrev_i32_e32 v35, 31, v34
	v_mul_lo_u32 v36, s26, v35
	v_mul_lo_u32 v37, s27, v34
	v_mad_u64_u32 v[34:35], s[30:31], s26, v34, 0
	v_add3_u32 v35, v35, v36, v37
	v_lshl_add_u64 v[34:35], v[34:35], 2, v[74:75]
	global_load_dwordx4 v[34:37], v[34:35], off nt
.LBB0_179:
	s_or_b64 exec, exec, s[24:25]
	v_mov_b32_e32 v42, 0
	v_mov_b32_e32 v46, 0
	v_mov_b32_e32 v47, 0
	v_mov_b32_e32 v48, 0
	v_mov_b32_e32 v49, 0
	s_and_saveexec_b64 s[24:25], vcc
	s_cbranch_execz .LBB0_181
	v_add_u32_e32 v43, 64, v0
	v_ashrrev_i32_e32 v44, 31, v43
	v_mul_lo_u32 v46, s26, v44
	v_mul_lo_u32 v47, s27, v43
	v_mad_u64_u32 v[44:45], s[30:31], s26, v43, 0
	v_add3_u32 v45, v45, v46, v47
	v_lshl_add_u64 v[44:45], v[44:45], 2, v[74:75]
	global_load_dwordx4 v[46:49], v[44:45], off nt
.LBB0_181:
	s_or_b64 exec, exec, s[24:25]
	v_mov_b32_e32 v43, 0
	v_mov_b32_e32 v44, 0
	v_mov_b32_e32 v45, 0
	s_and_saveexec_b64 s[24:25], vcc
	s_cbranch_execz .LBB0_183
	v_add_u32_e32 v42, 0x60, v0
	v_ashrrev_i32_e32 v43, 31, v42
	v_mul_lo_u32 v44, s26, v43
	v_mul_lo_u32 v45, s27, v42
	v_mad_u64_u32 v[42:43], s[30:31], s26, v42, 0
	v_add3_u32 v43, v43, v44, v45
	v_lshl_add_u64 v[42:43], v[42:43], 2, v[74:75]
	global_load_dwordx4 v[42:45], v[42:43], off nt
.LBB0_183:
	s_or_b64 exec, exec, s[24:25]
	v_mov_b32_e32 v50, 0
	v_mov_b32_e32 v58, 0
	v_mov_b32_e32 v59, 0
	v_mov_b32_e32 v60, 0
	v_mov_b32_e32 v61, 0
	s_and_saveexec_b64 s[24:25], vcc
	s_cbranch_execz .LBB0_185
	v_add_u32_e32 v51, 0x80, v0
	v_ashrrev_i32_e32 v52, 31, v51
	v_mul_lo_u32 v54, s26, v52
	v_mul_lo_u32 v55, s27, v51
	v_mad_u64_u32 v[52:53], s[30:31], s26, v51, 0
	v_add3_u32 v53, v53, v54, v55
	v_lshl_add_u64 v[52:53], v[52:53], 2, v[74:75]
	global_load_dwordx4 v[58:61], v[52:53], off nt
.LBB0_185:
	s_or_b64 exec, exec, s[24:25]
	v_mov_b32_e32 v51, 0
	v_mov_b32_e32 v52, 0
	v_mov_b32_e32 v53, 0
	s_and_saveexec_b64 s[24:25], vcc
	s_cbranch_execz .LBB0_187
	v_add_u32_e32 v50, 0xa0, v0
	v_ashrrev_i32_e32 v51, 31, v50
	v_mul_lo_u32 v52, s26, v51
	v_mul_lo_u32 v53, s27, v50
	v_mad_u64_u32 v[50:51], s[30:31], s26, v50, 0
	v_add3_u32 v51, v51, v52, v53
	v_lshl_add_u64 v[50:51], v[50:51], 2, v[74:75]
	global_load_dwordx4 v[50:53], v[50:51], off nt
.LBB0_187:
	s_or_b64 exec, exec, s[24:25]
	v_mov_b32_e32 v57, 0
	v_mov_b32_e32 v62, 0
	v_mov_b32_e32 v63, 0
	v_mov_b32_e32 v64, 0
	v_mov_b32_e32 v65, 0
	s_and_saveexec_b64 s[24:25], vcc
	s_cbranch_execz .LBB0_189
	v_add_u32_e32 v54, 0xc0, v0
	v_ashrrev_i32_e32 v55, 31, v54
	v_mul_lo_u32 v56, s26, v55
	v_mul_lo_u32 v62, s27, v54
	v_mad_u64_u32 v[54:55], s[30:31], s26, v54, 0
	v_add3_u32 v55, v55, v56, v62
	v_lshl_add_u64 v[54:55], v[54:55], 2, v[74:75]
	global_load_dwordx4 v[62:65], v[54:55], off nt
.LBB0_189:
	s_or_b64 exec, exec, s[24:25]
	v_mov_b32_e32 v56, 0
	v_mov_b32_e32 v55, 0
	v_mov_b32_e32 v54, 0
	s_and_saveexec_b64 s[24:25], vcc
	s_cbranch_execz .LBB0_191
	v_add_u32_e32 v0, 0xe0, v0
	v_ashrrev_i32_e32 v54, 31, v0
	v_mul_lo_u32 v56, s26, v54
	v_mul_lo_u32 v57, s27, v0
	v_mad_u64_u32 v[54:55], s[26:27], s26, v0, 0
	v_add3_u32 v55, v55, v56, v57
	v_lshl_add_u64 v[54:55], v[54:55], 2, v[74:75]
	global_load_dwordx4 v[54:57], v[54:55], off nt
